# static priority scheme (flips removed, waves 4-7 raised once) also in the P1 GEMM K-loop
# baseline (speedup 1.0000x reference)
;     __host__ __device__ bool next(int i, Unit& u) const { const long L = (long)i * so.G + so.c; if (L < so.nwg) return so.next(i, u); if (L >= so.nwg + extra) return false; u.pm = so.nM + (int)(L - so.nwg); u.pn = so.nN - 1; return true; }
; #define PG8_STAGE(bufoff, gbase, voff) do { _Pragma("unroll") for (int _i = 0; _i < 2; ++_i) \
;         __builtin_amdgcn_global_load_lds((const unsigned*)((const char*)(gbase) + (voff)[_i]), (PG8_LAS unsigned*)(lds + (bufoff) + ldsw + _i * 8192), 16, 0, 0); } while (0)
; #define PG8_LDA(dst, b, h) do { _Pragma("unroll") for (int m = 0; m < 4; ++m) _Pragma("unroll") for (int k = 0; k < 2; ++k) dst[m][k] = *(const PG8_LAS bf16x8*)(lds + PG8_SA(b, h) + aoff + m * 2048 + k * 1024); } while (0)
; #define PG8_LDB(dst, b, h) do { _Pragma("unroll") for (int n = 0; n < 2; ++n) _Pragma("unroll") for (int k = 0; k < 2; ++k) dst[n][k] = *(const PG8_LAS bf16x8*)(lds + PG8_SB(b, h) + boff + n * 2048 + k * 1024); } while (0)
; #define PG8_SCHED __builtin_amdgcn_sched_barrier(0)
; template <class Epi, class Sched, bool ALIGN_EPI = false, bool SP2 = false>
; __device__ __forceinline__ void gemm_phase(PG8_LAS unsigned char* lds, const Gemm g, const Sched& S, const Epi& E) {
;     ...
;     for (;;) {
;         const bool has_next = S.next(ui + 1, nxt);
;         const char* nA = has_next ? (const char*)g.A + (size_t)nxt.pm * tstepA : cA; const char* nB = has_next ? (const char*)g.Bt + (size_t)nxt.pn * tstep : cB;
;         for (int t = 0; t < nt; t += 2) {
;             const bool last = (t == nt - 2);
;             const char* a1 = cA + (size_t)(t + 1) * kstep;
;             const char* a2 = last ? nA : cA + (size_t)(t + 2) * kstep; const char* b2 = last ? nB : cB + (size_t)(t + 2) * kstep;
;             const char* a3 = a2 + kstep; const char* b3 = b2 + kstep;
;             if (last && has_next) S.a_ready(nxt);
;             if constexpr (SP2) {
;             PG8_LDB(B0, 0, 0); PG8_LDB(B1, 0, 1); PG8_SCHED; PG8_LDA(At, 0, 0); PG8_STAGE(PG8_SA(1, 1), a1 + hstepA, voffA);
.LBB0_56:
	s_ashr_i32 s21, s20, 31
	s_lshl_b64 s[16:17], s[20:21], 19
	s_add_u32 s22, s6, s16
	s_addc_u32 s23, s7, s17
	s_and_b64 s[16:17], s[4:5], exec
	s_cselect_b32 s21, s23, s29
	s_cselect_b32 s55, s22, s28
	s_ashr_i32 s19, s18, 31
	s_lshl_b64 s[16:17], s[18:19], 19
	s_add_u32 s24, s3, s16
	s_addc_u32 s25, s33, s17
	s_and_b64 s[16:17], s[4:5], exec
	s_cselect_b32 s19, s25, s31
	s_cselect_b32 s56, s24, s30
	s_add_u32 s28, s28, 0x40080
	s_addc_u32 s29, s29, 0
	s_add_u32 s57, s30, 0x100
	v_mov_b32_e32 v0, 0
	s_addc_u32 s58, s31, 0
	s_mov_b32 s59, -2
	v_mov_b32_e32 v1, v0
	v_mov_b32_e32 v2, v0
	v_mov_b32_e32 v3, v0
	v_mov_b32_e32 v4, v0
	v_mov_b32_e32 v5, v0
	v_mov_b32_e32 v6, v0
	v_mov_b32_e32 v7, v0
	v_mov_b32_e32 v8, v0
	v_mov_b32_e32 v9, v0
	v_mov_b32_e32 v10, v0
	v_mov_b32_e32 v11, v0
	v_mov_b32_e32 v16, v0
	v_mov_b32_e32 v17, v0
	v_mov_b32_e32 v18, v0
	v_mov_b32_e32 v19, v0
	v_mov_b32_e32 v24, v0
	v_mov_b32_e32 v25, v0
	v_mov_b32_e32 v26, v0
	v_mov_b32_e32 v27, v0
	v_mov_b32_e32 v32, v0
	v_mov_b32_e32 v33, v0
	v_mov_b32_e32 v34, v0
	v_mov_b32_e32 v35, v0
	v_mov_b32_e32 v40, v0
	v_mov_b32_e32 v41, v0
	v_mov_b32_e32 v42, v0
	v_mov_b32_e32 v43, v0
	v_mov_b32_e32 v48, v0
	v_mov_b32_e32 v49, v0
	v_mov_b32_e32 v50, v0
	v_mov_b32_e32 v51, v0
	v_mov_b32_e32 v12, v0
	v_mov_b32_e32 v13, v0
	v_mov_b32_e32 v14, v0
	v_mov_b32_e32 v15, v0
	v_mov_b32_e32 v20, v0
	v_mov_b32_e32 v21, v0
	v_mov_b32_e32 v22, v0
	v_mov_b32_e32 v23, v0
	v_mov_b32_e32 v28, v0
	v_mov_b32_e32 v29, v0
	v_mov_b32_e32 v30, v0
	v_mov_b32_e32 v31, v0
	v_mov_b32_e32 v36, v0
	v_mov_b32_e32 v37, v0
	v_mov_b32_e32 v38, v0
	v_mov_b32_e32 v39, v0
	v_mov_b32_e32 v44, v0
	v_mov_b32_e32 v45, v0
	v_mov_b32_e32 v46, v0
	v_mov_b32_e32 v47, v0
	v_mov_b32_e32 v52, v0
	v_mov_b32_e32 v53, v0
	v_mov_b32_e32 v54, v0
	v_mov_b32_e32 v55, v0
	v_mov_b32_e32 v56, v0
	v_mov_b32_e32 v57, v0
	v_mov_b32_e32 v58, v0
	v_mov_b32_e32 v59, v0
	v_mov_b32_e32 v60, v0
	v_mov_b32_e32 v61, v0
	v_mov_b32_e32 v62, v0
	v_mov_b32_e32 v63, v0
	v_mov_b32_e32 v64, v0
	v_mov_b32_e32 v65, v0
	v_mov_b32_e32 v66, v0
	v_mov_b32_e32 v67, v0
	v_mov_b32_e32 v68, v0
	v_mov_b32_e32 v69, v0
	v_mov_b32_e32 v70, v0
	v_mov_b32_e32 v71, v0
	v_mov_b32_e32 v72, v0
	v_mov_b32_e32 v73, v0
	v_mov_b32_e32 v74, v0
	v_mov_b32_e32 v75, v0
	v_mov_b32_e32 v80, v0
	v_mov_b32_e32 v81, v0
	v_mov_b32_e32 v82, v0
	v_mov_b32_e32 v83, v0
	v_mov_b32_e32 v88, v0
	v_mov_b32_e32 v89, v0
	v_mov_b32_e32 v90, v0
	v_mov_b32_e32 v91, v0
	v_mov_b32_e32 v96, v0
	v_mov_b32_e32 v97, v0
	v_mov_b32_e32 v98, v0
	v_mov_b32_e32 v99, v0
	v_mov_b32_e32 v104, v0
	v_mov_b32_e32 v105, v0
	v_mov_b32_e32 v106, v0
	v_mov_b32_e32 v107, v0
	v_mov_b32_e32 v112, v0
	v_mov_b32_e32 v113, v0
	v_mov_b32_e32 v114, v0
	v_mov_b32_e32 v115, v0
	v_mov_b32_e32 v76, v0
	v_mov_b32_e32 v77, v0
	v_mov_b32_e32 v78, v0
	v_mov_b32_e32 v79, v0
	v_mov_b32_e32 v84, v0
	v_mov_b32_e32 v85, v0
	v_mov_b32_e32 v86, v0
	v_mov_b32_e32 v87, v0
	v_mov_b32_e32 v92, v0
	v_mov_b32_e32 v93, v0
	v_mov_b32_e32 v94, v0
	v_mov_b32_e32 v95, v0
	v_mov_b32_e32 v100, v0
	v_mov_b32_e32 v101, v0
	v_mov_b32_e32 v102, v0
	v_mov_b32_e32 v103, v0
	v_mov_b32_e32 v108, v0
	v_mov_b32_e32 v109, v0
	v_mov_b32_e32 v110, v0
	v_mov_b32_e32 v111, v0
	v_mov_b32_e32 v116, v0
	v_mov_b32_e32 v117, v0
	v_mov_b32_e32 v118, v0
	v_mov_b32_e32 v119, v0
	v_mov_b32_e32 v120, v0
	v_mov_b32_e32 v121, v0
	v_mov_b32_e32 v122, v0
	v_mov_b32_e32 v123, v0
	v_mov_b32_e32 v124, v0
	v_mov_b32_e32 v125, v0
	v_mov_b32_e32 v126, v0
	v_mov_b32_e32 v127, v0
	v_readfirstlane_b32 s98, v162
	s_nop 3
	s_cmp_ge_u32 s98, 0x100
	s_cbranch_scc0 .Lprio_done_57
	s_setprio 1
.Lprio_done_57:
.LBB0_57:
	ds_read_b128 v[144:147], v152
	ds_read_b128 v[156:159], v152 offset:1024
	ds_read_b128 v[164:167], v152 offset:2048
	ds_read_b128 v[168:171], v152 offset:3072
	ds_read_b128 v[172:175], v153
	ds_read_b128 v[176:179], v153 offset:1024
	ds_read_b128 v[180:183], v153 offset:2048
	ds_read_b128 v[184:187], v153 offset:3072
	s_add_u32 s16, s28, 0xfffc0080
	s_addc_u32 s17, s29, -1
	s_cmp_eq_u32 s59, 12
	s_cselect_b32 s35, s21, s17
	s_cselect_b32 s34, s55, s16
	s_cselect_b32 s31, s19, s58
	s_cselect_b32 s30, s56, s57
	v_lshl_add_u64 v[160:161], s[28:29], 0, v[136:137]
	s_add_i32 m0, s27, 0xc000
	ds_read_b128 v[188:191], v154
	ds_read_b128 v[192:195], v154 offset:1024
	ds_read_b128 v[196:199], v154 offset:2048
	ds_read_b128 v[200:203], v154 offset:3072
	ds_read_b128 v[204:207], v154 offset:4096
	ds_read_b128 v[208:211], v154 offset:5120
	ds_read_b128 v[212:215], v154 offset:6144
	ds_read_b128 v[216:219], v154 offset:7168
	global_load_lds_dwordx4 v[160:161], off
	v_lshl_add_u64 v[160:161], s[28:29], 0, v[138:139]
	s_add_i32 m0, s27, 0xe000
	s_nop 0
	global_load_lds_dwordx4 v[160:161], off
	s_waitcnt vmcnt(8)
	s_waitcnt lgkmcnt(0)
	s_barrier
; #define PG8_STAGE(bufoff, gbase, voff) do { _Pragma("unroll") for (int _i = 0; _i < 2; ++_i) \
;         __builtin_amdgcn_global_load_lds((const unsigned*)((const char*)(gbase) + (voff)[_i]), (PG8_LAS unsigned*)(lds + (bufoff) + ldsw + _i * 8192), 16, 0, 0); } while (0)
; #define PG8_LDA(dst, b, h) do { _Pragma("unroll") for (int m = 0; m < 4; ++m) _Pragma("unroll") for (int k = 0; k < 2; ++k) dst[m][k] = *(const PG8_LAS bf16x8*)(lds + PG8_SA(b, h) + aoff + m * 2048 + k * 1024); } while (0)
; #define PG8_MMA(ai, bj, At, Bt) do { __builtin_amdgcn_s_setprio(1); _Pragma("unroll") for (int m = 0; m < 4; ++m) _Pragma("unroll") for (int n = 0; n < 2; ++n) _Pragma("unroll") for (int k = 0; k < 2; ++k) \
;         acc[ai][bj][m][n] = __builtin_amdgcn_mfma_f32_16x16x32_bf16(Bt[n][k], At[m][k], acc[ai][bj][m][n], 0, 0, 0); __builtin_amdgcn_s_setprio(0); } while (0)
; #define PG8_WAIT_V(n) asm volatile("s_waitcnt vmcnt(" #n ")" ::: "memory")
; #define PG8_WAIT_L(n) asm volatile("s_waitcnt lgkmcnt(" #n ")" ::: "memory")
; #define PG8_BAR __builtin_amdgcn_s_barrier()
; #define PG8_SCHED __builtin_amdgcn_sched_barrier(0)
; template <class Epi, class Sched, bool ALIGN_EPI = false, bool SP2 = false>
; __device__ __forceinline__ void gemm_phase(PG8_LAS unsigned char* lds, const Gemm g, const Sched& S, const Epi& E) {
;     ...
;             PG8_WAIT_V(8); PG8_WAIT_L(0); PG8_BAR; PG8_MMA(0, 0, At, B0); PG8_MMA(0, 1, At, B1); PG8_BAR; PG8_SCHED;
;             PG8_LDA(At, 0, 1); PG8_STAGE(PG8_SB(0, 0), b2, voffB); PG8_STAGE(PG8_SB(0, 1), b2 + hstep, voffB); PG8_STAGE(PG8_SA(0, 0), a2, voffA);
;             PG8_WAIT_V(8); PG8_WAIT_L(0); PG8_BAR; PG8_MMA(1, 0, At, B0); PG8_MMA(1, 1, At, B1); PG8_BAR; PG8_SCHED;
	s_waitcnt lgkmcnt(0)
	v_mfma_f32_16x16x32_bf16 v[124:127], v[144:147], v[188:191], v[124:127]
	v_mfma_f32_16x16x32_bf16 v[120:123], v[164:167], v[188:191], v[120:123]
	v_mfma_f32_16x16x32_bf16 v[116:119], v[144:147], v[196:199], v[116:119]
	v_mfma_f32_16x16x32_bf16 v[108:111], v[164:167], v[196:199], v[108:111]
	v_mfma_f32_16x16x32_bf16 v[100:103], v[144:147], v[204:207], v[100:103]
	v_mfma_f32_16x16x32_bf16 v[92:95], v[164:167], v[204:207], v[92:95]
	v_mfma_f32_16x16x32_bf16 v[84:87], v[144:147], v[212:215], v[84:87]
	v_mfma_f32_16x16x32_bf16 v[76:79], v[164:167], v[212:215], v[76:79]
	v_mfma_f32_16x16x32_bf16 v[124:127], v[156:159], v[192:195], v[124:127]
	v_mfma_f32_16x16x32_bf16 v[120:123], v[168:171], v[192:195], v[120:123]
	v_mfma_f32_16x16x32_bf16 v[116:119], v[156:159], v[200:203], v[116:119]
	v_mfma_f32_16x16x32_bf16 v[108:111], v[168:171], v[200:203], v[108:111]
	v_mfma_f32_16x16x32_bf16 v[100:103], v[156:159], v[208:211], v[100:103]
	v_mfma_f32_16x16x32_bf16 v[92:95], v[168:171], v[208:211], v[92:95]
	v_mfma_f32_16x16x32_bf16 v[84:87], v[156:159], v[216:219], v[84:87]
	v_mfma_f32_16x16x32_bf16 v[76:79], v[168:171], v[216:219], v[76:79]
	v_mfma_f32_16x16x32_bf16 v[112:115], v[172:175], v[188:191], v[112:115]
	v_mfma_f32_16x16x32_bf16 v[104:107], v[180:183], v[188:191], v[104:107]
	v_mfma_f32_16x16x32_bf16 v[96:99], v[172:175], v[196:199], v[96:99]
	v_mfma_f32_16x16x32_bf16 v[88:91], v[180:183], v[196:199], v[88:91]
	v_mfma_f32_16x16x32_bf16 v[80:83], v[172:175], v[204:207], v[80:83]
	v_mfma_f32_16x16x32_bf16 v[72:75], v[180:183], v[204:207], v[72:75]
	v_mfma_f32_16x16x32_bf16 v[68:71], v[172:175], v[212:215], v[68:71]
	v_mfma_f32_16x16x32_bf16 v[64:67], v[180:183], v[212:215], v[64:67]
	v_mfma_f32_16x16x32_bf16 v[112:115], v[176:179], v[192:195], v[112:115]
	v_mfma_f32_16x16x32_bf16 v[104:107], v[184:187], v[192:195], v[104:107]
	v_mfma_f32_16x16x32_bf16 v[96:99], v[176:179], v[200:203], v[96:99]
	v_mfma_f32_16x16x32_bf16 v[88:91], v[184:187], v[200:203], v[88:91]
	v_mfma_f32_16x16x32_bf16 v[80:83], v[176:179], v[208:211], v[80:83]
	v_mfma_f32_16x16x32_bf16 v[72:75], v[184:187], v[208:211], v[72:75]
	v_mfma_f32_16x16x32_bf16 v[68:71], v[176:179], v[216:219], v[68:71]
	v_mfma_f32_16x16x32_bf16 v[64:67], v[184:187], v[216:219], v[64:67]
	s_barrier
	s_add_i32 s16, s49, s36
	v_lshl_add_u64 v[160:161], s[30:31], 0, v[132:133]
	s_mov_b32 m0, s16
	ds_read_b128 v[188:191], v154 offset:16384
	ds_read_b128 v[192:195], v154 offset:17408
	ds_read_b128 v[196:199], v154 offset:18432
	ds_read_b128 v[200:203], v154 offset:19456
	ds_read_b128 v[204:207], v154 offset:20480
	ds_read_b128 v[208:211], v154 offset:21504
	ds_read_b128 v[212:215], v154 offset:22528
	ds_read_b128 v[216:219], v154 offset:23552
	global_load_lds_dwordx4 v[160:161], off
	s_add_i32 m0, s16, 0x2000
	s_add_u32 s16, s30, 0x40000
	v_lshl_add_u64 v[220:221], s[30:31], 0, v[128:129]
	s_addc_u32 s17, s31, 0
	s_add_i32 s60, s50, s36
	global_load_lds_dwordx4 v[220:221], off
	v_lshl_add_u64 v[222:223], s[16:17], 0, v[132:133]
	s_mov_b32 m0, s60
	v_lshl_add_u64 v[224:225], s[34:35], 0, v[130:131]
	global_load_lds_dwordx4 v[222:223], off
	v_lshl_add_u64 v[222:223], s[16:17], 0, v[128:129]
	s_add_i32 m0, s60, 0x2000
	s_nop 0
	global_load_lds_dwordx4 v[222:223], off
	v_lshl_add_u64 v[222:223], s[34:35], 0, v[134:135]
	s_mov_b32 m0, s27
	s_nop 0
	global_load_lds_dwordx4 v[222:223], off
	s_mov_b32 m0, s39
	s_nop 0
	global_load_lds_dwordx4 v[224:225], off
	s_waitcnt vmcnt(8)
	s_waitcnt lgkmcnt(0)
	s_barrier
	s_waitcnt lgkmcnt(0)
	v_mfma_f32_16x16x32_bf16 v[60:63], v[144:147], v[188:191], v[60:63]
	v_mfma_f32_16x16x32_bf16 v[56:59], v[164:167], v[188:191], v[56:59]
	v_mfma_f32_16x16x32_bf16 v[52:55], v[144:147], v[196:199], v[52:55]
	v_mfma_f32_16x16x32_bf16 v[44:47], v[164:167], v[196:199], v[44:47]
	v_mfma_f32_16x16x32_bf16 v[36:39], v[144:147], v[204:207], v[36:39]
	v_mfma_f32_16x16x32_bf16 v[28:31], v[164:167], v[204:207], v[28:31]
	v_mfma_f32_16x16x32_bf16 v[20:23], v[144:147], v[212:215], v[20:23]
	v_mfma_f32_16x16x32_bf16 v[12:15], v[164:167], v[212:215], v[12:15]
	v_mfma_f32_16x16x32_bf16 v[60:63], v[156:159], v[192:195], v[60:63]
	v_mfma_f32_16x16x32_bf16 v[56:59], v[168:171], v[192:195], v[56:59]
	v_mfma_f32_16x16x32_bf16 v[52:55], v[156:159], v[200:203], v[52:55]
	v_mfma_f32_16x16x32_bf16 v[44:47], v[168:171], v[200:203], v[44:47]
	v_mfma_f32_16x16x32_bf16 v[36:39], v[156:159], v[208:211], v[36:39]
	v_mfma_f32_16x16x32_bf16 v[28:31], v[168:171], v[208:211], v[28:31]
	v_mfma_f32_16x16x32_bf16 v[20:23], v[156:159], v[216:219], v[20:23]
	v_mfma_f32_16x16x32_bf16 v[12:15], v[168:171], v[216:219], v[12:15]
	v_mfma_f32_16x16x32_bf16 v[48:51], v[172:175], v[188:191], v[48:51]
	v_mfma_f32_16x16x32_bf16 v[40:43], v[180:183], v[188:191], v[40:43]
	v_mfma_f32_16x16x32_bf16 v[32:35], v[172:175], v[196:199], v[32:35]
	v_mfma_f32_16x16x32_bf16 v[24:27], v[180:183], v[196:199], v[24:27]
	v_mfma_f32_16x16x32_bf16 v[16:19], v[172:175], v[204:207], v[16:19]
	v_mfma_f32_16x16x32_bf16 v[8:11], v[180:183], v[204:207], v[8:11]
	v_mfma_f32_16x16x32_bf16 v[4:7], v[172:175], v[212:215], v[4:7]
	v_mfma_f32_16x16x32_bf16 v[0:3], v[180:183], v[212:215], v[0:3]
	v_mfma_f32_16x16x32_bf16 v[48:51], v[176:179], v[192:195], v[48:51]
	v_mfma_f32_16x16x32_bf16 v[40:43], v[184:187], v[192:195], v[40:43]
	v_mfma_f32_16x16x32_bf16 v[32:35], v[176:179], v[200:203], v[32:35]
	v_mfma_f32_16x16x32_bf16 v[24:27], v[184:187], v[200:203], v[24:27]
	v_mfma_f32_16x16x32_bf16 v[16:19], v[176:179], v[208:211], v[16:19]
	v_mfma_f32_16x16x32_bf16 v[8:11], v[184:187], v[208:211], v[8:11]
	v_mfma_f32_16x16x32_bf16 v[4:7], v[176:179], v[216:219], v[4:7]
	v_mfma_f32_16x16x32_bf16 v[0:3], v[184:187], v[216:219], v[0:3]
	s_barrier
; #define PG8_STAGE(bufoff, gbase, voff) do { _Pragma("unroll") for (int _i = 0; _i < 2; ++_i) \
;         __builtin_amdgcn_global_load_lds((const unsigned*)((const char*)(gbase) + (voff)[_i]), (PG8_LAS unsigned*)(lds + (bufoff) + ldsw + _i * 8192), 16, 0, 0); } while (0)
; #define PG8_LDA(dst, b, h) do { _Pragma("unroll") for (int m = 0; m < 4; ++m) _Pragma("unroll") for (int k = 0; k < 2; ++k) dst[m][k] = *(const PG8_LAS bf16x8*)(lds + PG8_SA(b, h) + aoff + m * 2048 + k * 1024); } while (0)
; #define PG8_LDB(dst, b, h) do { _Pragma("unroll") for (int n = 0; n < 2; ++n) _Pragma("unroll") for (int k = 0; k < 2; ++k) dst[n][k] = *(const PG8_LAS bf16x8*)(lds + PG8_SB(b, h) + boff + n * 2048 + k * 1024); } while (0)
; #define PG8_MMA(ai, bj, At, Bt) do { __builtin_amdgcn_s_setprio(1); _Pragma("unroll") for (int m = 0; m < 4; ++m) _Pragma("unroll") for (int n = 0; n < 2; ++n) _Pragma("unroll") for (int k = 0; k < 2; ++k) \
;         acc[ai][bj][m][n] = __builtin_amdgcn_mfma_f32_16x16x32_bf16(Bt[n][k], At[m][k], acc[ai][bj][m][n], 0, 0, 0); __builtin_amdgcn_s_setprio(0); } while (0)
; #define PG8_WAIT_V(n) asm volatile("s_waitcnt vmcnt(" #n ")" ::: "memory")
; #define PG8_WAIT_L(n) asm volatile("s_waitcnt lgkmcnt(" #n ")" ::: "memory")
; #define PG8_BAR __builtin_amdgcn_s_barrier()
; #define PG8_SCHED __builtin_amdgcn_sched_barrier(0)
; template <class Epi, class Sched, bool ALIGN_EPI = false, bool SP2 = false>
; __device__ __forceinline__ void gemm_phase(PG8_LAS unsigned char* lds, const Gemm g, const Sched& S, const Epi& E) {
;     ...
;             PG8_LDB(B0, 1, 0); PG8_LDB(B1, 1, 1); PG8_SCHED; PG8_LDA(At, 1, 0); PG8_STAGE(PG8_SA(0, 1), a2 + hstepA, voffA);
;             PG8_WAIT_V(8); PG8_WAIT_L(0); PG8_BAR; PG8_MMA(0, 0, At, B0); PG8_MMA(0, 1, At, B1); PG8_BAR; PG8_SCHED;
	s_add_i32 s60, 0, 0x18000
	v_add_u32_e32 v155, s60, v150
	s_add_i32 s61, 0, 0x1c000
	ds_read_b128 v[144:147], v155
	ds_read_b128 v[156:159], v155 offset:1024
	ds_read_b128 v[164:167], v155 offset:2048
	ds_read_b128 v[168:171], v155 offset:3072
	v_add_u32_e32 v155, s61, v150
	ds_read_b128 v[172:175], v155
	ds_read_b128 v[176:179], v155 offset:1024
	ds_read_b128 v[180:183], v155 offset:2048
	ds_read_b128 v[184:187], v155 offset:3072
	s_add_u32 s16, s34, 0x40000
	s_addc_u32 s17, s35, 0
	s_mov_b32 m0, s40
	v_lshl_add_u64 v[226:227], s[16:17], 0, v[134:135]
	ds_read_b128 v[188:191], v154 offset:32768
	ds_read_b128 v[192:195], v154 offset:33792
	ds_read_b128 v[196:199], v154 offset:34816
	ds_read_b128 v[200:203], v154 offset:35840
	ds_read_b128 v[204:207], v154 offset:36864
	ds_read_b128 v[208:211], v154 offset:37888
	ds_read_b128 v[212:215], v154 offset:38912
	ds_read_b128 v[216:219], v154 offset:39936
	global_load_lds_dwordx4 v[226:227], off
	v_lshl_add_u64 v[226:227], s[16:17], 0, v[130:131]
	s_mov_b32 m0, s41
	s_nop 0
	global_load_lds_dwordx4 v[226:227], off
	s_waitcnt vmcnt(8)
	s_waitcnt lgkmcnt(0)
	s_barrier
	s_waitcnt lgkmcnt(0)
	v_mfma_f32_16x16x32_bf16 v[124:127], v[144:147], v[188:191], v[124:127]
	v_mfma_f32_16x16x32_bf16 v[120:123], v[164:167], v[188:191], v[120:123]
	v_mfma_f32_16x16x32_bf16 v[116:119], v[144:147], v[196:199], v[116:119]
	v_mfma_f32_16x16x32_bf16 v[108:111], v[164:167], v[196:199], v[108:111]
	v_mfma_f32_16x16x32_bf16 v[100:103], v[144:147], v[204:207], v[100:103]
	v_mfma_f32_16x16x32_bf16 v[92:95], v[164:167], v[204:207], v[92:95]
	v_mfma_f32_16x16x32_bf16 v[84:87], v[144:147], v[212:215], v[84:87]
	v_mfma_f32_16x16x32_bf16 v[76:79], v[164:167], v[212:215], v[76:79]
	v_mfma_f32_16x16x32_bf16 v[124:127], v[156:159], v[192:195], v[124:127]
	v_mfma_f32_16x16x32_bf16 v[120:123], v[168:171], v[192:195], v[120:123]
	v_mfma_f32_16x16x32_bf16 v[116:119], v[156:159], v[200:203], v[116:119]
	v_mfma_f32_16x16x32_bf16 v[108:111], v[168:171], v[200:203], v[108:111]
	v_mfma_f32_16x16x32_bf16 v[100:103], v[156:159], v[208:211], v[100:103]
	v_mfma_f32_16x16x32_bf16 v[92:95], v[168:171], v[208:211], v[92:95]
	v_mfma_f32_16x16x32_bf16 v[84:87], v[156:159], v[216:219], v[84:87]
	v_mfma_f32_16x16x32_bf16 v[76:79], v[168:171], v[216:219], v[76:79]
	v_mfma_f32_16x16x32_bf16 v[112:115], v[172:175], v[188:191], v[112:115]
	v_mfma_f32_16x16x32_bf16 v[104:107], v[180:183], v[188:191], v[104:107]
	v_mfma_f32_16x16x32_bf16 v[96:99], v[172:175], v[196:199], v[96:99]
	v_mfma_f32_16x16x32_bf16 v[88:91], v[180:183], v[196:199], v[88:91]
	v_mfma_f32_16x16x32_bf16 v[80:83], v[172:175], v[204:207], v[80:83]
	v_mfma_f32_16x16x32_bf16 v[72:75], v[180:183], v[204:207], v[72:75]
	v_mfma_f32_16x16x32_bf16 v[68:71], v[172:175], v[212:215], v[68:71]
	v_mfma_f32_16x16x32_bf16 v[64:67], v[180:183], v[212:215], v[64:67]
	v_mfma_f32_16x16x32_bf16 v[112:115], v[176:179], v[192:195], v[112:115]
	v_mfma_f32_16x16x32_bf16 v[104:107], v[184:187], v[192:195], v[104:107]
	v_mfma_f32_16x16x32_bf16 v[96:99], v[176:179], v[200:203], v[96:99]
	v_mfma_f32_16x16x32_bf16 v[88:91], v[184:187], v[200:203], v[88:91]
	v_mfma_f32_16x16x32_bf16 v[80:83], v[176:179], v[208:211], v[80:83]
	v_mfma_f32_16x16x32_bf16 v[72:75], v[184:187], v[208:211], v[72:75]
	v_mfma_f32_16x16x32_bf16 v[68:71], v[176:179], v[216:219], v[68:71]
	v_mfma_f32_16x16x32_bf16 v[64:67], v[184:187], v[216:219], v[64:67]
	s_barrier
; #define PG8_STAGE(bufoff, gbase, voff) do { _Pragma("unroll") for (int _i = 0; _i < 2; ++_i) \
;         __builtin_amdgcn_global_load_lds((const unsigned*)((const char*)(gbase) + (voff)[_i]), (PG8_LAS unsigned*)(lds + (bufoff) + ldsw + _i * 8192), 16, 0, 0); } while (0)
; #define PG8_LDA(dst, b, h) do { _Pragma("unroll") for (int m = 0; m < 4; ++m) _Pragma("unroll") for (int k = 0; k < 2; ++k) dst[m][k] = *(const PG8_LAS bf16x8*)(lds + PG8_SA(b, h) + aoff + m * 2048 + k * 1024); } while (0)
; #define PG8_MMA(ai, bj, At, Bt) do { __builtin_amdgcn_s_setprio(1); _Pragma("unroll") for (int m = 0; m < 4; ++m) _Pragma("unroll") for (int n = 0; n < 2; ++n) _Pragma("unroll") for (int k = 0; k < 2; ++k) \
;         acc[ai][bj][m][n] = __builtin_amdgcn_mfma_f32_16x16x32_bf16(Bt[n][k], At[m][k], acc[ai][bj][m][n], 0, 0, 0); __builtin_amdgcn_s_setprio(0); } while (0)
; #define PG8_WAIT_V(n) asm volatile("s_waitcnt vmcnt(" #n ")" ::: "memory")
; #define PG8_WAIT_L(n) asm volatile("s_waitcnt lgkmcnt(" #n ")" ::: "memory")
; #define PG8_BAR __builtin_amdgcn_s_barrier()
; #define PG8_SCHED __builtin_amdgcn_sched_barrier(0)
; template <class Epi, class Sched, bool ALIGN_EPI = false, bool SP2 = false>
; __device__ __forceinline__ void gemm_phase(PG8_LAS unsigned char* lds, const Gemm g, const Sched& S, const Epi& E) {
;     ...
;         for (int t = 0; t < nt; t += 2) {
;     ...
;             PG8_LDA(At, 1, 1); PG8_STAGE(PG8_SB(1, 0), b3, voffB); PG8_STAGE(PG8_SB(1, 1), b3 + hstep, voffB); PG8_STAGE(PG8_SA(1, 0), a3, voffA);
;             PG8_WAIT_V(8); PG8_WAIT_L(0); PG8_BAR; PG8_MMA(1, 0, At, B0); PG8_MMA(1, 1, At, B1); PG8_BAR; PG8_SCHED;
	s_add_i32 s16, s60, s36
	v_lshl_add_u64 v[160:161], v[160:161], 0, s[12:13]
	s_mov_b32 m0, s16
	ds_read_b128 v[188:191], v154 offset:49152
	ds_read_b128 v[192:195], v154 offset:50176
	ds_read_b128 v[196:199], v154 offset:51200
	ds_read_b128 v[200:203], v154 offset:52224
	ds_read_b128 v[204:207], v154 offset:53248
	ds_read_b128 v[208:211], v154 offset:54272
	ds_read_b128 v[212:215], v154 offset:55296
	ds_read_b128 v[216:219], v154 offset:56320
	global_load_lds_dwordx4 v[160:161], off
	s_add_i32 m0, s16, 0x2000
	s_add_u32 s16, s30, 0x40080
	v_lshl_add_u64 v[160:161], v[220:221], 0, s[12:13]
	s_addc_u32 s17, s31, 0
	s_add_i32 s30, s61, s36
	global_load_lds_dwordx4 v[160:161], off
	v_lshl_add_u64 v[160:161], s[16:17], 0, v[132:133]
	s_mov_b32 m0, s30
	s_nop 0
	global_load_lds_dwordx4 v[160:161], off
	v_lshl_add_u64 v[160:161], s[16:17], 0, v[128:129]
	s_add_i32 m0, s30, 0x2000
	s_nop 0
	global_load_lds_dwordx4 v[160:161], off
	v_lshl_add_u64 v[160:161], v[222:223], 0, s[12:13]
	s_mov_b32 m0, s45
	s_nop 0
	global_load_lds_dwordx4 v[160:161], off
	v_lshl_add_u64 v[160:161], v[224:225], 0, s[12:13]
	s_mov_b32 m0, s46
	s_nop 0
	global_load_lds_dwordx4 v[160:161], off
	s_waitcnt vmcnt(8)
	s_waitcnt lgkmcnt(0)
	s_barrier
	s_waitcnt lgkmcnt(0)
	v_mfma_f32_16x16x32_bf16 v[60:63], v[144:147], v[188:191], v[60:63]
	v_mfma_f32_16x16x32_bf16 v[56:59], v[164:167], v[188:191], v[56:59]
	v_mfma_f32_16x16x32_bf16 v[52:55], v[144:147], v[196:199], v[52:55]
	v_mfma_f32_16x16x32_bf16 v[44:47], v[164:167], v[196:199], v[44:47]
	v_mfma_f32_16x16x32_bf16 v[36:39], v[144:147], v[204:207], v[36:39]
	v_mfma_f32_16x16x32_bf16 v[28:31], v[164:167], v[204:207], v[28:31]
	v_mfma_f32_16x16x32_bf16 v[20:23], v[144:147], v[212:215], v[20:23]
	v_mfma_f32_16x16x32_bf16 v[12:15], v[164:167], v[212:215], v[12:15]
	v_mfma_f32_16x16x32_bf16 v[60:63], v[156:159], v[192:195], v[60:63]
	v_mfma_f32_16x16x32_bf16 v[56:59], v[168:171], v[192:195], v[56:59]
	v_mfma_f32_16x16x32_bf16 v[52:55], v[156:159], v[200:203], v[52:55]
	v_mfma_f32_16x16x32_bf16 v[44:47], v[168:171], v[200:203], v[44:47]
	v_mfma_f32_16x16x32_bf16 v[36:39], v[156:159], v[208:211], v[36:39]
	v_mfma_f32_16x16x32_bf16 v[28:31], v[168:171], v[208:211], v[28:31]
	v_mfma_f32_16x16x32_bf16 v[20:23], v[156:159], v[216:219], v[20:23]
	v_mfma_f32_16x16x32_bf16 v[12:15], v[168:171], v[216:219], v[12:15]
	v_mfma_f32_16x16x32_bf16 v[48:51], v[172:175], v[188:191], v[48:51]
	v_mfma_f32_16x16x32_bf16 v[40:43], v[180:183], v[188:191], v[40:43]
	v_mfma_f32_16x16x32_bf16 v[32:35], v[172:175], v[196:199], v[32:35]
	v_mfma_f32_16x16x32_bf16 v[24:27], v[180:183], v[196:199], v[24:27]
	v_mfma_f32_16x16x32_bf16 v[16:19], v[172:175], v[204:207], v[16:19]
	v_mfma_f32_16x16x32_bf16 v[8:11], v[180:183], v[204:207], v[8:11]
	v_mfma_f32_16x16x32_bf16 v[4:7], v[172:175], v[212:215], v[4:7]
	v_mfma_f32_16x16x32_bf16 v[0:3], v[180:183], v[212:215], v[0:3]
	v_mfma_f32_16x16x32_bf16 v[48:51], v[176:179], v[192:195], v[48:51]
	v_mfma_f32_16x16x32_bf16 v[40:43], v[184:187], v[192:195], v[40:43]
	v_mfma_f32_16x16x32_bf16 v[32:35], v[176:179], v[200:203], v[32:35]
	v_mfma_f32_16x16x32_bf16 v[24:27], v[184:187], v[200:203], v[24:27]
	v_mfma_f32_16x16x32_bf16 v[16:19], v[176:179], v[208:211], v[16:19]
	v_mfma_f32_16x16x32_bf16 v[8:11], v[184:187], v[208:211], v[8:11]
	v_mfma_f32_16x16x32_bf16 v[4:7], v[176:179], v[216:219], v[4:7]
	v_mfma_f32_16x16x32_bf16 v[0:3], v[184:187], v[216:219], v[0:3]
	s_barrier
	s_add_i32 s59, s59, 2
	s_add_u32 s28, s28, 0x100
	s_addc_u32 s29, s29, 0
	s_add_u32 s57, s57, 0x100
	s_addc_u32 s58, s58, 0
	s_cmp_gt_u32 s59, 13
	s_cbranch_scc0 .LBB0_57
	s_setprio 0
	s_and_b64 vcc, exec, s[14:15]
	s_cbranch_vccz .LBB0_60
	s_barrier
